# v112 + DSA item: waves 4-7 (second wave of each SIMD) at s_setprio 1 from the top-k phase to the end of the sparse attention, so their gather phase overlaps the other wave's VALU-bound top-k
# speedup vs baseline: 1.0062x; 1.0040x over previous
; #define LAS __attribute__((address_space(3)))
; __device__ __forceinline__ unsigned sortable(float f) { const unsigned b = __float_as_uint(f); return (b & 0x80000000u) ? ~b : (b | 0x80000000u); }
;     ...
;     const int pos = t0 + wid, n = pos + 1, kcount = n < 256 ? n : 256;
;     const size_t qgrow = (size_t)pos;
;     LAS unsigned char* wbase = lds + wid * 16384;
;     LAS unsigned char* aux = lds + B_OLAT + wid * 2048;
;     LAS u16* list = (LAS u16*)aux; LAS float* pbuf = (LAS float*)(aux + 1024); LAS float* alf = (LAS float*)(aux + 640);
;     { unsigned u[64];
;       LAS float* srow = sc + wid * 4096;
; #pragma unroll
;       for (int r = 0; r < 64; ++r) { u[r] = 0u; if (r * 64 < n) { const float f = srow[r * 64 + lane]; u[r] = (r * 64 + lane < n) ? sortable(f) : 0u; } }
.LBB0_198:
	s_add_i32 s61, s64, s30
	s_lshl_b32 s0, s64, 14
	s_add_i32 s60, s0, 0
	v_cmp_lt_i32_e64 s[0:1], s61, v163
	v_cmp_ge_i32_e32 vcc, s61, v163
	v_mov_b32_e32 v5, 0
	v_writelane_b32 v254, s0, 0
	v_mov_b32_e32 v6, 0
	s_waitcnt lgkmcnt(0)
	v_writelane_b32 v254, s1, 1
	s_barrier
	s_cmp_lt_u32 s59, 0x100
	s_cbranch_scc1 .Ldsa_prio_skip
	s_setprio 1
.Ldsa_prio_skip:
	s_cmp_gt_i32 s61, 63
	s_cselect_b64 s[0:1], -1, 0
	v_writelane_b32 v254, s0, 2
	s_nop 1
	v_writelane_b32 v254, s1, 3
	s_cmpk_gt_i32 s61, 0x7f
	s_cselect_b64 s[0:1], -1, 0
	v_writelane_b32 v254, s0, 4
	s_nop 1
	v_writelane_b32 v254, s1, 5
	s_cmpk_gt_i32 s61, 0xbf
	s_cselect_b64 s[0:1], -1, 0
	v_writelane_b32 v254, s0, 6
	s_nop 1
	v_writelane_b32 v254, s1, 7
	s_cmpk_gt_i32 s61, 0xff
	s_cselect_b64 s[0:1], -1, 0
	v_writelane_b32 v254, s0, 8
	s_nop 1
	v_writelane_b32 v254, s1, 9
	s_cmpk_gt_i32 s61, 0x13f
	s_cselect_b64 s[0:1], -1, 0
	v_writelane_b32 v254, s0, 10
	s_nop 1
	v_writelane_b32 v254, s1, 11
	s_cmpk_gt_i32 s61, 0x17f
	s_cselect_b64 s[0:1], -1, 0
	v_writelane_b32 v254, s0, 12
	s_nop 1
	v_writelane_b32 v254, s1, 13
	s_cmpk_gt_i32 s61, 0x1bf
	s_cselect_b64 s[0:1], -1, 0
	v_writelane_b32 v254, s0, 14
	s_nop 1
	v_writelane_b32 v254, s1, 15
	s_cmpk_gt_i32 s61, 0x1ff
	s_cselect_b64 s[0:1], -1, 0
	v_writelane_b32 v254, s0, 16
	s_nop 1
	v_writelane_b32 v254, s1, 17
	s_cmpk_gt_i32 s61, 0x23f
	s_cselect_b64 s[0:1], -1, 0
	v_writelane_b32 v254, s0, 18
	s_nop 1
	v_writelane_b32 v254, s1, 19
	s_cmpk_gt_i32 s61, 0x27f
	s_cselect_b64 s[0:1], -1, 0
	v_writelane_b32 v254, s0, 20
	s_nop 1
	v_writelane_b32 v254, s1, 21
	s_cmpk_gt_i32 s61, 0x2bf
	s_cselect_b64 s[0:1], -1, 0
	v_writelane_b32 v254, s0, 22
	s_nop 1
	v_writelane_b32 v254, s1, 23
	s_cmpk_gt_i32 s61, 0x2ff
	s_cselect_b64 s[0:1], -1, 0
	v_writelane_b32 v254, s0, 24
	s_nop 1
	v_writelane_b32 v254, s1, 25
	s_cmpk_gt_i32 s61, 0x33f
	s_cselect_b64 s[0:1], -1, 0
	v_writelane_b32 v254, s0, 26
	s_nop 1
	v_writelane_b32 v254, s1, 27
	s_cmpk_gt_i32 s61, 0x37f
	s_cselect_b64 s[0:1], -1, 0
	v_writelane_b32 v254, s0, 28
	s_nop 1
	v_writelane_b32 v254, s1, 29
	s_cmpk_gt_i32 s61, 0x3bf
	s_cselect_b64 s[0:1], -1, 0
	v_writelane_b32 v254, s0, 30
	s_nop 1
	v_writelane_b32 v254, s1, 31
	s_cmpk_gt_i32 s61, 0x3ff
	s_cselect_b64 s[0:1], -1, 0
	v_writelane_b32 v254, s0, 32
	s_nop 1
	v_writelane_b32 v254, s1, 33
	s_cmpk_gt_i32 s61, 0x43f
	s_cselect_b64 s[0:1], -1, 0
	v_writelane_b32 v254, s0, 34
	s_nop 1
	v_writelane_b32 v254, s1, 35
	s_cmpk_gt_i32 s61, 0x47f
	s_cselect_b64 s[0:1], -1, 0
	v_writelane_b32 v254, s0, 36
	s_nop 1
	v_writelane_b32 v254, s1, 37
	s_cmpk_gt_i32 s61, 0x4bf
	s_cselect_b64 s[0:1], -1, 0
	v_writelane_b32 v254, s0, 38
	s_nop 1
	v_writelane_b32 v254, s1, 39
	s_cmpk_gt_i32 s61, 0x4ff
	s_cselect_b64 s[0:1], -1, 0
	v_writelane_b32 v254, s0, 40
	s_nop 1
	v_writelane_b32 v254, s1, 41
	s_cmpk_gt_i32 s61, 0x53f
	s_cselect_b64 s[0:1], -1, 0
	v_writelane_b32 v254, s0, 42
	s_nop 1
	v_writelane_b32 v254, s1, 43
	s_cmpk_gt_i32 s61, 0x57f
	s_cselect_b64 s[0:1], -1, 0
	v_writelane_b32 v254, s0, 44
	s_nop 1
	v_writelane_b32 v254, s1, 45
	s_cmpk_gt_i32 s61, 0x5bf
	s_cselect_b64 s[0:1], -1, 0
	v_writelane_b32 v254, s0, 46
	s_nop 1
	v_writelane_b32 v254, s1, 47
	s_cmpk_gt_i32 s61, 0x5ff
	s_cselect_b64 s[0:1], -1, 0
	v_writelane_b32 v254, s0, 48
	s_nop 1
	v_writelane_b32 v254, s1, 49
	s_cmpk_gt_i32 s61, 0x63f
	s_cselect_b64 s[0:1], -1, 0
	v_writelane_b32 v254, s0, 50
	s_nop 1
	v_writelane_b32 v254, s1, 51
	s_cmpk_gt_i32 s61, 0x67f
	s_cselect_b64 s[0:1], -1, 0
	v_writelane_b32 v254, s0, 52
	s_nop 1
	v_writelane_b32 v254, s1, 53
	s_cmpk_gt_i32 s61, 0x6bf
	s_cselect_b64 s[0:1], -1, 0
	v_writelane_b32 v254, s0, 54
	s_nop 1
	v_writelane_b32 v254, s1, 55
	s_cmpk_gt_i32 s61, 0x6ff
	s_cselect_b64 s[0:1], -1, 0
	v_writelane_b32 v254, s0, 56
	s_nop 1
	v_writelane_b32 v254, s1, 57
	s_cmpk_gt_i32 s61, 0x73f
	s_cselect_b64 s[0:1], -1, 0
	v_writelane_b32 v254, s0, 58
	s_nop 1
	v_writelane_b32 v254, s1, 59
	s_cmpk_gt_i32 s61, 0x77f
	s_cselect_b64 s[0:1], -1, 0
	v_writelane_b32 v254, s0, 60
	s_nop 1
	v_writelane_b32 v254, s1, 61
	s_cmpk_gt_i32 s61, 0x7bf
	s_cselect_b64 s[0:1], -1, 0
	v_writelane_b32 v254, s0, 62
	s_nop 1
	v_writelane_b32 v254, s1, 63
	s_cmpk_gt_i32 s61, 0x7ff
	s_cselect_b64 s[0:1], -1, 0
	v_writelane_b32 v250, s0, 0
	s_nop 1
	v_writelane_b32 v250, s1, 1
	s_cmpk_gt_i32 s61, 0x83f
	s_cselect_b64 s[0:1], -1, 0
	v_writelane_b32 v250, s0, 2
	s_nop 1
	v_writelane_b32 v250, s1, 3
	s_cmpk_gt_i32 s61, 0x87f
	s_cselect_b64 s[0:1], -1, 0
	v_writelane_b32 v250, s0, 4
	s_nop 1
	v_writelane_b32 v250, s1, 5
	s_cmpk_gt_i32 s61, 0x8bf
	s_cselect_b64 s[0:1], -1, 0
	v_writelane_b32 v250, s0, 6
	s_nop 1
	v_writelane_b32 v250, s1, 7
	s_cmpk_gt_i32 s61, 0x8ff
	s_cselect_b64 s[0:1], -1, 0
	v_writelane_b32 v250, s0, 8
	s_nop 1
	v_writelane_b32 v250, s1, 9
	s_cmpk_gt_i32 s61, 0x93f
	s_cselect_b64 s[0:1], -1, 0
	v_writelane_b32 v250, s0, 10
	s_nop 1
	v_writelane_b32 v250, s1, 11
	s_cmpk_gt_i32 s61, 0x97f
	s_cselect_b64 s[0:1], -1, 0
	v_writelane_b32 v250, s0, 12
	s_nop 1
	v_writelane_b32 v250, s1, 13
	s_cmpk_gt_i32 s61, 0x9bf
	s_cselect_b64 s[0:1], -1, 0
	v_writelane_b32 v250, s0, 14
	s_nop 1
	v_writelane_b32 v250, s1, 15
	s_cmpk_gt_i32 s61, 0x9ff
	s_cselect_b64 s[0:1], -1, 0
	v_writelane_b32 v250, s0, 16
	s_nop 1
	v_writelane_b32 v250, s1, 17
	s_cmpk_gt_i32 s61, 0xa3f
	s_cselect_b64 s[0:1], -1, 0
	v_writelane_b32 v250, s0, 18
	s_nop 1
	v_writelane_b32 v250, s1, 19
	s_cmpk_gt_i32 s61, 0xa7f
	s_cselect_b64 s[0:1], -1, 0
	v_writelane_b32 v250, s0, 20
	s_nop 1
	v_writelane_b32 v250, s1, 21
	s_cmpk_gt_i32 s61, 0xabf
	s_cselect_b64 s[0:1], -1, 0
	v_writelane_b32 v250, s0, 22
; #define LAS __attribute__((address_space(3)))
; __device__ __forceinline__ unsigned sortable(float f) { const unsigned b = __float_as_uint(f); return (b & 0x80000000u) ? ~b : (b | 0x80000000u); }
;     ...
;     { unsigned u[64];
;       LAS float* srow = sc + wid * 4096;
; #pragma unroll
;       for (int r = 0; r < 64; ++r) { u[r] = 0u; if (r * 64 < n) { const float f = srow[r * 64 + lane]; u[r] = (r * 64 + lane < n) ? sortable(f) : 0u; } }
;       const int nreg = (n + 63) >> 6;
	s_nop 1
	v_writelane_b32 v250, s1, 23
	s_cmpk_gt_i32 s61, 0xaff
	s_cselect_b64 s[0:1], -1, 0
	v_writelane_b32 v250, s0, 24
	s_nop 1
	v_writelane_b32 v250, s1, 25
	s_cmpk_gt_i32 s61, 0xb3f
	s_cselect_b64 s[0:1], -1, 0
	v_writelane_b32 v250, s0, 26
	s_nop 1
	v_writelane_b32 v250, s1, 27
	s_cmpk_gt_i32 s61, 0xb7f
	s_cselect_b64 s[0:1], -1, 0
	v_writelane_b32 v250, s0, 28
	s_nop 1
	v_writelane_b32 v250, s1, 29
	s_cmpk_gt_i32 s61, 0xbbf
	s_cselect_b64 s[0:1], -1, 0
	v_writelane_b32 v250, s0, 30
	s_nop 1
	v_writelane_b32 v250, s1, 31
	s_cmpk_gt_i32 s61, 0xbff
	s_cselect_b64 s[52:53], -1, 0
	s_cmpk_gt_i32 s61, 0xc3f
	s_cselect_b64 s[50:51], -1, 0
	s_cmpk_gt_i32 s61, 0xc7f
	s_cselect_b64 s[48:49], -1, 0
	s_cmpk_gt_i32 s61, 0xcbf
	s_cselect_b64 s[46:47], -1, 0
	s_cmpk_gt_i32 s61, 0xcff
	s_cselect_b64 s[42:43], -1, 0
	s_cmpk_gt_i32 s61, 0xd3f
	s_cselect_b64 s[40:41], -1, 0
	s_cmpk_gt_i32 s61, 0xd7f
	s_cselect_b64 s[38:39], -1, 0
	s_cmpk_gt_i32 s61, 0xdbf
	s_cselect_b64 s[82:83], -1, 0
	s_cmpk_gt_i32 s61, 0xdff
	s_cselect_b64 s[96:97], -1, 0
	s_cmpk_gt_i32 s61, 0xe3f
	s_cselect_b64 s[94:95], -1, 0
	s_cmpk_gt_i32 s61, 0xe7f
	s_cselect_b64 s[92:93], -1, 0
	s_cmpk_gt_i32 s61, 0xebf
	s_cselect_b64 s[76:77], -1, 0
	s_cmpk_gt_i32 s61, 0xeff
	s_cselect_b64 s[90:91], -1, 0
	s_cmpk_gt_i32 s61, 0xf3f
	s_cselect_b64 s[88:89], -1, 0
	s_cmpk_gt_i32 s61, 0xf7f
	s_cselect_b64 s[86:87], -1, 0
	s_cmpk_gt_i32 s61, 0xfbf
	s_cselect_b64 s[84:85], -1, 0
	s_waitcnt vmcnt(0)
	v_lshl_add_u32 v0, v163, 2, s60
	v_sub_u32_e32 v2, s61, v163
	ds_read_b32 v6, v0
	ds_read_b32 v5, v0 offset:256
	ds_read_b32 v8, v0 offset:512
	ds_read_b32 v7, v0 offset:768
	ds_read_b32 v10, v0 offset:1024
	ds_read_b32 v9, v0 offset:1280
	ds_read_b32 v12, v0 offset:1536
	ds_read_b32 v11, v0 offset:1792
	ds_read_b32 v14, v0 offset:2048
	ds_read_b32 v13, v0 offset:2304
	ds_read_b32 v16, v0 offset:2560
	ds_read_b32 v15, v0 offset:2816
	ds_read_b32 v18, v0 offset:3072
	ds_read_b32 v17, v0 offset:3328
	ds_read_b32 v20, v0 offset:3584
	s_waitcnt lgkmcnt(0)
	s_cmpk_lt_i32 s61, 0x3c0
	s_cbranch_scc1 .Ludsa_last0
	ds_read_b32 v19, v0 offset:3840
	ds_read_b32 v22, v0 offset:4096
	ds_read_b32 v21, v0 offset:4352
	ds_read_b32 v24, v0 offset:4608
	ds_read_b32 v23, v0 offset:4864
	ds_read_b32 v26, v0 offset:5120
	ds_read_b32 v25, v0 offset:5376
	ds_read_b32 v28, v0 offset:5632
	ds_read_b32 v27, v0 offset:5888
	ds_read_b32 v30, v0 offset:6144
	ds_read_b32 v29, v0 offset:6400
	ds_read_b32 v32, v0 offset:6656
	ds_read_b32 v31, v0 offset:6912
	ds_read_b32 v34, v0 offset:7168
	ds_read_b32 v33, v0 offset:7424
	v_cmp_le_i32_e32 vcc, 0, v2
	v_ashrrev_i32_e32 v4, 31, v6
	v_or_b32_e32 v4, 0x80000000, v4
	v_xor_b32_e32 v6, v4, v6
	v_cndmask_b32_e32 v6, 0, v6, vcc
	v_cmp_le_i32_e32 vcc, 64, v2
	v_ashrrev_i32_e32 v3, 31, v5
	v_or_b32_e32 v3, 0x80000000, v3
	v_xor_b32_e32 v5, v3, v5
	v_cndmask_b32_e32 v5, 0, v5, vcc
	v_cmp_le_i32_e32 vcc, 0x80, v2
	v_ashrrev_i32_e32 v4, 31, v8
	v_or_b32_e32 v4, 0x80000000, v4
	v_xor_b32_e32 v8, v4, v8
	v_cndmask_b32_e32 v8, 0, v8, vcc
	v_cmp_le_i32_e32 vcc, 0xc0, v2
	v_ashrrev_i32_e32 v3, 31, v7
	v_or_b32_e32 v3, 0x80000000, v3
	v_xor_b32_e32 v7, v3, v7
	v_cndmask_b32_e32 v7, 0, v7, vcc
	v_cmp_le_i32_e32 vcc, 0x100, v2
	v_ashrrev_i32_e32 v4, 31, v10
	v_or_b32_e32 v4, 0x80000000, v4
	v_xor_b32_e32 v10, v4, v10
	v_cndmask_b32_e32 v10, 0, v10, vcc
	v_cmp_le_i32_e32 vcc, 0x140, v2
	v_ashrrev_i32_e32 v3, 31, v9
	v_or_b32_e32 v3, 0x80000000, v3
	v_xor_b32_e32 v9, v3, v9
	v_cndmask_b32_e32 v9, 0, v9, vcc
	v_cmp_le_i32_e32 vcc, 0x180, v2
	v_ashrrev_i32_e32 v4, 31, v12
	v_or_b32_e32 v4, 0x80000000, v4
	v_xor_b32_e32 v12, v4, v12
	v_cndmask_b32_e32 v12, 0, v12, vcc
	v_cmp_le_i32_e32 vcc, 0x1c0, v2
	v_ashrrev_i32_e32 v3, 31, v11
	v_or_b32_e32 v3, 0x80000000, v3
	v_xor_b32_e32 v11, v3, v11
	v_cndmask_b32_e32 v11, 0, v11, vcc
	v_cmp_le_i32_e32 vcc, 0x200, v2
	v_ashrrev_i32_e32 v4, 31, v14
	v_or_b32_e32 v4, 0x80000000, v4
	v_xor_b32_e32 v14, v4, v14
	v_cndmask_b32_e32 v14, 0, v14, vcc
	v_cmp_le_i32_e32 vcc, 0x240, v2
	v_ashrrev_i32_e32 v3, 31, v13
	v_or_b32_e32 v3, 0x80000000, v3
	v_xor_b32_e32 v13, v3, v13
	v_cndmask_b32_e32 v13, 0, v13, vcc
	v_cmp_le_i32_e32 vcc, 0x280, v2
	v_ashrrev_i32_e32 v4, 31, v16
	v_or_b32_e32 v4, 0x80000000, v4
	v_xor_b32_e32 v16, v4, v16
	v_cndmask_b32_e32 v16, 0, v16, vcc
	v_cmp_le_i32_e32 vcc, 0x2c0, v2
	v_ashrrev_i32_e32 v3, 31, v15
	v_or_b32_e32 v3, 0x80000000, v3
	v_xor_b32_e32 v15, v3, v15
	v_cndmask_b32_e32 v15, 0, v15, vcc
	v_cmp_le_i32_e32 vcc, 0x300, v2
	v_ashrrev_i32_e32 v4, 31, v18
	v_or_b32_e32 v4, 0x80000000, v4
	v_xor_b32_e32 v18, v4, v18
	v_cndmask_b32_e32 v18, 0, v18, vcc
	v_cmp_le_i32_e32 vcc, 0x340, v2
	v_ashrrev_i32_e32 v3, 31, v17
	v_or_b32_e32 v3, 0x80000000, v3
	v_xor_b32_e32 v17, v3, v17
	v_cndmask_b32_e32 v17, 0, v17, vcc
	v_cmp_le_i32_e32 vcc, 0x380, v2
	v_ashrrev_i32_e32 v4, 31, v20
	v_or_b32_e32 v4, 0x80000000, v4
	v_xor_b32_e32 v20, v4, v20
	v_cndmask_b32_e32 v20, 0, v20, vcc
	s_waitcnt lgkmcnt(0)
	s_cmpk_lt_i32 s61, 0x780
	s_cbranch_scc1 .Ludsa_last1
; #define LAS __attribute__((address_space(3)))
; __device__ __forceinline__ unsigned sortable(float f) { const unsigned b = __float_as_uint(f); return (b & 0x80000000u) ? ~b : (b | 0x80000000u); }
;     ...
;     { unsigned u[64];
;       LAS float* srow = sc + wid * 4096;
; #pragma unroll
;       for (int r = 0; r < 64; ++r) { u[r] = 0u; if (r * 64 < n) { const float f = srow[r * 64 + lane]; u[r] = (r * 64 + lane < n) ? sortable(f) : 0u; } }
	ds_read_b32 v36, v0 offset:7680
	ds_read_b32 v35, v0 offset:7936
	ds_read_b32 v38, v0 offset:8192
	ds_read_b32 v37, v0 offset:8448
	ds_read_b32 v40, v0 offset:8704
	ds_read_b32 v39, v0 offset:8960
	ds_read_b32 v42, v0 offset:9216
	ds_read_b32 v41, v0 offset:9472
	ds_read_b32 v44, v0 offset:9728
	ds_read_b32 v43, v0 offset:9984
	ds_read_b32 v46, v0 offset:10240
	ds_read_b32 v45, v0 offset:10496
	ds_read_b32 v48, v0 offset:10752
	ds_read_b32 v47, v0 offset:11008
	ds_read_b32 v50, v0 offset:11264
	v_cmp_le_i32_e32 vcc, 0x3c0, v2
	v_ashrrev_i32_e32 v3, 31, v19
	v_or_b32_e32 v3, 0x80000000, v3
	v_xor_b32_e32 v19, v3, v19
	v_cndmask_b32_e32 v19, 0, v19, vcc
	v_cmp_le_i32_e32 vcc, 0x400, v2
	v_ashrrev_i32_e32 v4, 31, v22
	v_or_b32_e32 v4, 0x80000000, v4
	v_xor_b32_e32 v22, v4, v22
	v_cndmask_b32_e32 v22, 0, v22, vcc
	v_cmp_le_i32_e32 vcc, 0x440, v2
	v_ashrrev_i32_e32 v3, 31, v21
	v_or_b32_e32 v3, 0x80000000, v3
	v_xor_b32_e32 v21, v3, v21
	v_cndmask_b32_e32 v21, 0, v21, vcc
	v_cmp_le_i32_e32 vcc, 0x480, v2
	v_ashrrev_i32_e32 v4, 31, v24
	v_or_b32_e32 v4, 0x80000000, v4
	v_xor_b32_e32 v24, v4, v24
	v_cndmask_b32_e32 v24, 0, v24, vcc
	v_cmp_le_i32_e32 vcc, 0x4c0, v2
	v_ashrrev_i32_e32 v3, 31, v23
	v_or_b32_e32 v3, 0x80000000, v3
	v_xor_b32_e32 v23, v3, v23
	v_cndmask_b32_e32 v23, 0, v23, vcc
	v_cmp_le_i32_e32 vcc, 0x500, v2
	v_ashrrev_i32_e32 v4, 31, v26
	v_or_b32_e32 v4, 0x80000000, v4
	v_xor_b32_e32 v26, v4, v26
	v_cndmask_b32_e32 v26, 0, v26, vcc
	v_cmp_le_i32_e32 vcc, 0x540, v2
	v_ashrrev_i32_e32 v3, 31, v25
	v_or_b32_e32 v3, 0x80000000, v3
	v_xor_b32_e32 v25, v3, v25
	v_cndmask_b32_e32 v25, 0, v25, vcc
	v_cmp_le_i32_e32 vcc, 0x580, v2
	v_ashrrev_i32_e32 v4, 31, v28
	v_or_b32_e32 v4, 0x80000000, v4
	v_xor_b32_e32 v28, v4, v28
	v_cndmask_b32_e32 v28, 0, v28, vcc
	v_cmp_le_i32_e32 vcc, 0x5c0, v2
	v_ashrrev_i32_e32 v3, 31, v27
	v_or_b32_e32 v3, 0x80000000, v3
	v_xor_b32_e32 v27, v3, v27
	v_cndmask_b32_e32 v27, 0, v27, vcc
	v_cmp_le_i32_e32 vcc, 0x600, v2
	v_ashrrev_i32_e32 v4, 31, v30
	v_or_b32_e32 v4, 0x80000000, v4
	v_xor_b32_e32 v30, v4, v30
	v_cndmask_b32_e32 v30, 0, v30, vcc
	v_cmp_le_i32_e32 vcc, 0x640, v2
	v_ashrrev_i32_e32 v3, 31, v29
	v_or_b32_e32 v3, 0x80000000, v3
	v_xor_b32_e32 v29, v3, v29
	v_cndmask_b32_e32 v29, 0, v29, vcc
	v_cmp_le_i32_e32 vcc, 0x680, v2
	v_ashrrev_i32_e32 v4, 31, v32
	v_or_b32_e32 v4, 0x80000000, v4
	v_xor_b32_e32 v32, v4, v32
	v_cndmask_b32_e32 v32, 0, v32, vcc
	v_cmp_le_i32_e32 vcc, 0x6c0, v2
	v_ashrrev_i32_e32 v3, 31, v31
	v_or_b32_e32 v3, 0x80000000, v3
	v_xor_b32_e32 v31, v3, v31
	v_cndmask_b32_e32 v31, 0, v31, vcc
	v_cmp_le_i32_e32 vcc, 0x700, v2
	v_ashrrev_i32_e32 v4, 31, v34
	v_or_b32_e32 v4, 0x80000000, v4
	v_xor_b32_e32 v34, v4, v34
	v_cndmask_b32_e32 v34, 0, v34, vcc
	v_cmp_le_i32_e32 vcc, 0x740, v2
	v_ashrrev_i32_e32 v3, 31, v33
	v_or_b32_e32 v3, 0x80000000, v3
	v_xor_b32_e32 v33, v3, v33
	v_cndmask_b32_e32 v33, 0, v33, vcc
	s_waitcnt lgkmcnt(0)
	s_cmpk_lt_i32 s61, 0xb40
	s_cbranch_scc1 .Ludsa_last2
	ds_read_b32 v49, v0 offset:11520
	ds_read_b32 v52, v0 offset:11776
	ds_read_b32 v51, v0 offset:12032
	ds_read_b32 v54, v0 offset:12288
	ds_read_b32 v53, v0 offset:12544
	ds_read_b32 v56, v0 offset:12800
	ds_read_b32 v55, v0 offset:13056
	ds_read_b32 v58, v0 offset:13312
	ds_read_b32 v57, v0 offset:13568
	ds_read_b32 v60, v0 offset:13824
	ds_read_b32 v59, v0 offset:14080
	ds_read_b32 v62, v0 offset:14336
	ds_read_b32 v61, v0 offset:14592
	ds_read_b32 v64, v0 offset:14848
	ds_read_b32 v63, v0 offset:15104
	v_cmp_le_i32_e32 vcc, 0x780, v2
	v_ashrrev_i32_e32 v4, 31, v36
	v_or_b32_e32 v4, 0x80000000, v4
	v_xor_b32_e32 v36, v4, v36
	v_cndmask_b32_e32 v36, 0, v36, vcc
	v_cmp_le_i32_e32 vcc, 0x7c0, v2
	v_ashrrev_i32_e32 v3, 31, v35
	v_or_b32_e32 v3, 0x80000000, v3
	v_xor_b32_e32 v35, v3, v35
	v_cndmask_b32_e32 v35, 0, v35, vcc
	v_cmp_le_i32_e32 vcc, 0x800, v2
	v_ashrrev_i32_e32 v4, 31, v38
	v_or_b32_e32 v4, 0x80000000, v4
	v_xor_b32_e32 v38, v4, v38
	v_cndmask_b32_e32 v38, 0, v38, vcc
	v_cmp_le_i32_e32 vcc, 0x840, v2
	v_ashrrev_i32_e32 v3, 31, v37
	v_or_b32_e32 v3, 0x80000000, v3
	v_xor_b32_e32 v37, v3, v37
	v_cndmask_b32_e32 v37, 0, v37, vcc
	v_cmp_le_i32_e32 vcc, 0x880, v2
	v_ashrrev_i32_e32 v4, 31, v40
	v_or_b32_e32 v4, 0x80000000, v4
	v_xor_b32_e32 v40, v4, v40
	v_cndmask_b32_e32 v40, 0, v40, vcc
	v_cmp_le_i32_e32 vcc, 0x8c0, v2
	v_ashrrev_i32_e32 v3, 31, v39
	v_or_b32_e32 v3, 0x80000000, v3
	v_xor_b32_e32 v39, v3, v39
	v_cndmask_b32_e32 v39, 0, v39, vcc
	v_cmp_le_i32_e32 vcc, 0x900, v2
	v_ashrrev_i32_e32 v4, 31, v42
	v_or_b32_e32 v4, 0x80000000, v4
	v_xor_b32_e32 v42, v4, v42
	v_cndmask_b32_e32 v42, 0, v42, vcc
	v_cmp_le_i32_e32 vcc, 0x940, v2
	v_ashrrev_i32_e32 v3, 31, v41
	v_or_b32_e32 v3, 0x80000000, v3
	v_xor_b32_e32 v41, v3, v41
	v_cndmask_b32_e32 v41, 0, v41, vcc
	v_cmp_le_i32_e32 vcc, 0x980, v2
	v_ashrrev_i32_e32 v4, 31, v44
	v_or_b32_e32 v4, 0x80000000, v4
	v_xor_b32_e32 v44, v4, v44
	v_cndmask_b32_e32 v44, 0, v44, vcc
	v_cmp_le_i32_e32 vcc, 0x9c0, v2
	v_ashrrev_i32_e32 v3, 31, v43
	v_or_b32_e32 v3, 0x80000000, v3
	v_xor_b32_e32 v43, v3, v43
	v_cndmask_b32_e32 v43, 0, v43, vcc
	v_cmp_le_i32_e32 vcc, 0xa00, v2
	v_ashrrev_i32_e32 v4, 31, v46
	v_or_b32_e32 v4, 0x80000000, v4
	v_xor_b32_e32 v46, v4, v46
	v_cndmask_b32_e32 v46, 0, v46, vcc
	v_cmp_le_i32_e32 vcc, 0xa40, v2
	v_ashrrev_i32_e32 v3, 31, v45
	v_or_b32_e32 v3, 0x80000000, v3
	v_xor_b32_e32 v45, v3, v45
	v_cndmask_b32_e32 v45, 0, v45, vcc
	v_cmp_le_i32_e32 vcc, 0xa80, v2
	v_ashrrev_i32_e32 v4, 31, v48
	v_or_b32_e32 v4, 0x80000000, v4
	v_xor_b32_e32 v48, v4, v48
	v_cndmask_b32_e32 v48, 0, v48, vcc
	v_cmp_le_i32_e32 vcc, 0xac0, v2
	v_ashrrev_i32_e32 v3, 31, v47
	v_or_b32_e32 v3, 0x80000000, v3
	v_xor_b32_e32 v47, v3, v47
	v_cndmask_b32_e32 v47, 0, v47, vcc
	v_cmp_le_i32_e32 vcc, 0xb00, v2
	v_ashrrev_i32_e32 v4, 31, v50
	v_or_b32_e32 v4, 0x80000000, v4
	v_xor_b32_e32 v50, v4, v50
	v_cndmask_b32_e32 v50, 0, v50, vcc
	s_waitcnt lgkmcnt(0)
	s_cmpk_lt_i32 s61, 0xf00
	s_cbranch_scc1 .Ludsa_last3
; #define LAS __attribute__((address_space(3)))
; __device__ __forceinline__ unsigned sortable(float f) { const unsigned b = __float_as_uint(f); return (b & 0x80000000u) ? ~b : (b | 0x80000000u); }
;     ...
;     { unsigned u[64];
;       LAS float* srow = sc + wid * 4096;
; #pragma unroll
;       for (int r = 0; r < 64; ++r) { u[r] = 0u; if (r * 64 < n) { const float f = srow[r * 64 + lane]; u[r] = (r * 64 + lane < n) ? sortable(f) : 0u; } }
	ds_read_b32 v66, v0 offset:15360
	ds_read_b32 v65, v0 offset:15616
	ds_read_b32 v68, v0 offset:15872
	ds_read_b32 v67, v0 offset:16128
	v_cmp_le_i32_e32 vcc, 0xb40, v2
	v_ashrrev_i32_e32 v3, 31, v49
	v_or_b32_e32 v3, 0x80000000, v3
	v_xor_b32_e32 v49, v3, v49
	v_cndmask_b32_e32 v49, 0, v49, vcc
	v_cmp_le_i32_e32 vcc, 0xb80, v2
	v_ashrrev_i32_e32 v4, 31, v52
	v_or_b32_e32 v4, 0x80000000, v4
	v_xor_b32_e32 v52, v4, v52
	v_cndmask_b32_e32 v52, 0, v52, vcc
	v_cmp_le_i32_e32 vcc, 0xbc0, v2
	v_ashrrev_i32_e32 v3, 31, v51
	v_or_b32_e32 v3, 0x80000000, v3
	v_xor_b32_e32 v51, v3, v51
	v_cndmask_b32_e32 v51, 0, v51, vcc
	v_cmp_le_i32_e32 vcc, 0xc00, v2
	v_ashrrev_i32_e32 v4, 31, v54
	v_or_b32_e32 v4, 0x80000000, v4
	v_xor_b32_e32 v54, v4, v54
	v_cndmask_b32_e32 v54, 0, v54, vcc
	v_cmp_le_i32_e32 vcc, 0xc40, v2
	v_ashrrev_i32_e32 v3, 31, v53
	v_or_b32_e32 v3, 0x80000000, v3
	v_xor_b32_e32 v53, v3, v53
	v_cndmask_b32_e32 v53, 0, v53, vcc
	v_cmp_le_i32_e32 vcc, 0xc80, v2
	v_ashrrev_i32_e32 v4, 31, v56
	v_or_b32_e32 v4, 0x80000000, v4
	v_xor_b32_e32 v56, v4, v56
	v_cndmask_b32_e32 v56, 0, v56, vcc
	v_cmp_le_i32_e32 vcc, 0xcc0, v2
	v_ashrrev_i32_e32 v3, 31, v55
	v_or_b32_e32 v3, 0x80000000, v3
	v_xor_b32_e32 v55, v3, v55
	v_cndmask_b32_e32 v55, 0, v55, vcc
	v_cmp_le_i32_e32 vcc, 0xd00, v2
	v_ashrrev_i32_e32 v4, 31, v58
	v_or_b32_e32 v4, 0x80000000, v4
	v_xor_b32_e32 v58, v4, v58
	v_cndmask_b32_e32 v58, 0, v58, vcc
	v_cmp_le_i32_e32 vcc, 0xd40, v2
	v_ashrrev_i32_e32 v3, 31, v57
	v_or_b32_e32 v3, 0x80000000, v3
	v_xor_b32_e32 v57, v3, v57
	v_cndmask_b32_e32 v57, 0, v57, vcc
	v_cmp_le_i32_e32 vcc, 0xd80, v2
	v_ashrrev_i32_e32 v4, 31, v60
	v_or_b32_e32 v4, 0x80000000, v4
	v_xor_b32_e32 v60, v4, v60
	v_cndmask_b32_e32 v60, 0, v60, vcc
	v_cmp_le_i32_e32 vcc, 0xdc0, v2
	v_ashrrev_i32_e32 v3, 31, v59
	v_or_b32_e32 v3, 0x80000000, v3
	v_xor_b32_e32 v59, v3, v59
	v_cndmask_b32_e32 v59, 0, v59, vcc
	v_cmp_le_i32_e32 vcc, 0xe00, v2
	v_ashrrev_i32_e32 v4, 31, v62
	v_or_b32_e32 v4, 0x80000000, v4
	v_xor_b32_e32 v62, v4, v62
	v_cndmask_b32_e32 v62, 0, v62, vcc
	v_cmp_le_i32_e32 vcc, 0xe40, v2
	v_ashrrev_i32_e32 v3, 31, v61
	v_or_b32_e32 v3, 0x80000000, v3
	v_xor_b32_e32 v61, v3, v61
	v_cndmask_b32_e32 v61, 0, v61, vcc
	v_cmp_le_i32_e32 vcc, 0xe80, v2
	v_ashrrev_i32_e32 v4, 31, v64
	v_or_b32_e32 v4, 0x80000000, v4
	v_xor_b32_e32 v64, v4, v64
	v_cndmask_b32_e32 v64, 0, v64, vcc
	v_cmp_le_i32_e32 vcc, 0xec0, v2
	v_ashrrev_i32_e32 v3, 31, v63
	v_or_b32_e32 v3, 0x80000000, v3
	v_xor_b32_e32 v63, v3, v63
	v_cndmask_b32_e32 v63, 0, v63, vcc
	s_waitcnt lgkmcnt(0)
	v_cmp_le_i32_e32 vcc, 0xf00, v2
	v_ashrrev_i32_e32 v4, 31, v66
	v_or_b32_e32 v4, 0x80000000, v4
	v_xor_b32_e32 v66, v4, v66
	v_cndmask_b32_e32 v66, 0, v66, vcc
	v_cmp_le_i32_e32 vcc, 0xf40, v2
	v_ashrrev_i32_e32 v3, 31, v65
	v_or_b32_e32 v3, 0x80000000, v3
	v_xor_b32_e32 v65, v3, v65
	v_cndmask_b32_e32 v65, 0, v65, vcc
	v_cmp_le_i32_e32 vcc, 0xf80, v2
	v_ashrrev_i32_e32 v4, 31, v68
	v_or_b32_e32 v4, 0x80000000, v4
	v_xor_b32_e32 v68, v4, v68
	v_cndmask_b32_e32 v68, 0, v68, vcc
	v_cmp_le_i32_e32 vcc, 0xfc0, v2
	v_ashrrev_i32_e32 v3, 31, v67
	v_or_b32_e32 v3, 0x80000000, v3
	v_xor_b32_e32 v67, v3, v67
	v_cndmask_b32_e32 v67, 0, v67, vcc
	s_branch .Ludsa_done

; #define LAS __attribute__((address_space(3)))
;     ...
; #pragma unroll
;       for (int o = 1; o < 16; o <<= 1) lsum += __shfl_xor(lsum, o);
;       if (c16 == 0) alf[quad] = 1.f / lsum;
;       const f32x4 il4 = *(const LAS f32x4*)alf;
.LBB0_953:
	s_setprio 0
	s_nop 1
	v_add_f32_dpp v0, v118, v118 quad_perm:[1,0,3,2] row_mask:0xf bank_mask:0xf
	s_nop 1
	v_add_f32_dpp v0, v0, v0 quad_perm:[2,3,0,1] row_mask:0xf bank_mask:0xf
	s_nop 1
	v_add_f32_dpp v0, v0, v0 row_half_mirror row_mask:0xf bank_mask:0xf
	s_nop 1
	v_mov_b32_dpp v2, v0 row_mirror row_mask:0xf bank_mask:0xf
	v_cmp_eq_u32_e32 vcc, 0, v127
	s_and_saveexec_b64 s[0:1], vcc
	s_cbranch_execz .LBB0_955
	s_waitcnt lgkmcnt(0)
	v_add_f32_e32 v0, v0, v2
	v_div_scale_f32 v2, s[20:21], v0, v0, 1.0
	v_rcp_f32_e32 v3, v2
	v_div_scale_f32 v4, vcc, 1.0, v0, 1.0
	v_fma_f32 v5, -v2, v3, 1.0
	v_fmac_f32_e32 v3, v5, v3
	v_mul_f32_e32 v5, v4, v3
	v_fma_f32 v6, -v2, v5, v4
	v_fmac_f32_e32 v5, v6, v3
	v_fma_f32 v2, -v2, v5, v4
	v_div_fmas_f32 v2, v2, v3, v5
	v_div_fixup_f32 v0, v2, v0, 1.0
	ds_write_b32 v129, v0 offset:640
